# pool phase sample-tile path: state-sum loads and 14-row state copy issued as batches instead of load-wait-store chains
# baseline (speedup 1.0000x reference)
; __device__ __forceinline__ void phase_pool(Frame& F, const Params& p, int j, int first) {
;     ...
;             if (F.lane == 0) red[F.wave] = s;
;             __syncthreads();
;             s = 0.f;
; #pragma unroll
;             for (int q = 0; q < 8; ++q) s += red[q];
;             const f32x4 h = x * (1.0f / sqrtf(s * (1.0f / D) + EPS)) * g;
;             const float* st = p.in[2] + (size_t)(j * NSAMP + b) * 15 * D;
;             float* so = F.out + O_POOLS + (size_t)(j * NSAMP + b) * 15 * D;
;             const int w = 2 << (F.wave >> 1);
;             f32x4 sum = h;
;             for (int q = 1; q < w; ++q) sum += *((const f32x4*)(st + (size_t)(15 - q) * D) + c4);
.LBB0_45:
	s_or_b64 exec, exec, s[4:5]
	s_waitcnt lgkmcnt(0)
	s_barrier
	ds_read_b128 v[6:9], v143 offset:256
	ds_read_b128 v[10:13], v143 offset:272
	s_waitcnt lgkmcnt(1)
	v_add_f32_e32 v6, 0, v6
	v_add_f32_e32 v6, v6, v7
	v_add_f32_e32 v6, v6, v8
	v_add_f32_e32 v6, v6, v9
	s_waitcnt lgkmcnt(0)
	v_add_f32_e32 v6, v6, v10
	v_add_f32_e32 v6, v6, v11
	v_add_f32_e32 v6, v6, v12
	v_add_f32_e32 v6, v6, v13
	v_fmamk_f32 v6, v6, 0x3a000000, v152
	v_mul_f32_e32 v7, 0x4f800000, v6
	v_cmp_gt_f32_e32 vcc, s1, v6
	v_readlane_b32 s0, v254, 45
	v_readlane_b32 s1, v254, 46
	v_cndmask_b32_e32 v6, v6, v7, vcc
	v_sqrt_f32_e32 v7, v6
	s_nop 0
	v_add_u32_e32 v8, -1, v7
	v_fma_f32 v10, -v8, v7, v6
	v_add_u32_e32 v9, 1, v7
	v_cmp_ge_f32_e64 s[4:5], 0, v10
	s_nop 1
	v_cndmask_b32_e64 v8, v7, v8, s[4:5]
	v_fma_f32 v7, -v9, v7, v6
	v_cmp_lt_f32_e64 s[4:5], 0, v7
	s_nop 1
	v_cndmask_b32_e64 v7, v8, v9, s[4:5]
	v_mul_f32_e32 v8, 0x37800000, v7
	v_cndmask_b32_e32 v7, v7, v8, vcc
	v_cmp_class_f32_e32 vcc, v6, v153
	s_nop 1
	v_cndmask_b32_e32 v6, v7, v6, vcc
	v_div_scale_f32 v7, s[4:5], v6, v6, 1.0
	v_rcp_f32_e32 v8, v7
	s_nop 0
	v_fma_f32 v9, -v7, v8, 1.0
	v_fmac_f32_e32 v8, v9, v8
	v_div_scale_f32 v9, vcc, 1.0, v6, 1.0
	v_mul_f32_e32 v10, v9, v8
	v_fma_f32 v11, -v7, v10, v9
	v_fmac_f32_e32 v10, v11, v8
	v_fma_f32 v7, -v7, v10, v9
	v_div_fmas_f32 v7, v7, v8, v10
	v_div_fixup_f32 v6, v7, v6, 1.0
	v_pk_mul_f32 v[4:5], v[4:5], v[6:7] op_sel_hi:[1,0]
	v_pk_mul_f32 v[2:3], v[2:3], v[6:7] op_sel_hi:[1,0]
	v_pk_mul_f32 v[4:5], v[68:69], v[4:5]
	v_pk_mul_f32 v[2:3], v[66:67], v[2:3]
	s_andn2_b64 vcc, exec, s[0:1]
	v_mov_b64_e32 v[8:9], v[4:5]
	v_mov_b64_e32 v[6:7], v[2:3]
	s_cbranch_vccnz .LBB0_48
	v_mad_u64_u32 v[10:11], s[4:5], s28, v162, v[146:147]
	v_mov_b64_e32 v[8:9], v[4:5]
	s_mov_b32 s4, s37
	v_mov_b64_e32 v[6:7], v[2:3]
	s_cmp_gt_u32 s4, 0
	s_cbranch_scc0 .LpsA_ld
	global_load_dwordx4 v[16:19], v[10:11], off
	v_lshl_add_u64 v[10:11], v[10:11], 0, s[24:25]
	s_cmp_gt_u32 s4, 1
	s_cbranch_scc0 .LpsA_ld
	global_load_dwordx4 v[20:23], v[10:11], off
	v_lshl_add_u64 v[10:11], v[10:11], 0, s[24:25]
	s_cmp_gt_u32 s4, 2
	s_cbranch_scc0 .LpsA_ld
	global_load_dwordx4 v[24:27], v[10:11], off
	v_lshl_add_u64 v[10:11], v[10:11], 0, s[24:25]
	s_cmp_gt_u32 s4, 3
	s_cbranch_scc0 .LpsA_ld
	global_load_dwordx4 v[28:31], v[10:11], off
	v_lshl_add_u64 v[10:11], v[10:11], 0, s[24:25]
	s_cmp_gt_u32 s4, 4
	s_cbranch_scc0 .LpsA_ld
	global_load_dwordx4 v[32:35], v[10:11], off
	v_lshl_add_u64 v[10:11], v[10:11], 0, s[24:25]
	s_cmp_gt_u32 s4, 5
	s_cbranch_scc0 .LpsA_ld
	global_load_dwordx4 v[36:39], v[10:11], off
	v_lshl_add_u64 v[10:11], v[10:11], 0, s[24:25]
	s_cmp_gt_u32 s4, 6
	s_cbranch_scc0 .LpsA_ld
	global_load_dwordx4 v[40:43], v[10:11], off
	v_lshl_add_u64 v[10:11], v[10:11], 0, s[24:25]
	s_cmp_gt_u32 s4, 7
	s_cbranch_scc0 .LpsA_ld
	global_load_dwordx4 v[44:47], v[10:11], off
	v_lshl_add_u64 v[10:11], v[10:11], 0, s[24:25]
	s_cmp_gt_u32 s4, 8
	s_cbranch_scc0 .LpsA_ld
	global_load_dwordx4 v[48:51], v[10:11], off
	v_lshl_add_u64 v[10:11], v[10:11], 0, s[24:25]
	s_cmp_gt_u32 s4, 9
	s_cbranch_scc0 .LpsA_ld
	global_load_dwordx4 v[52:55], v[10:11], off
	v_lshl_add_u64 v[10:11], v[10:11], 0, s[24:25]
	s_cmp_gt_u32 s4, 10
	s_cbranch_scc0 .LpsA_ld
	global_load_dwordx4 v[56:59], v[10:11], off
	v_lshl_add_u64 v[10:11], v[10:11], 0, s[24:25]
	s_cmp_gt_u32 s4, 11
	s_cbranch_scc0 .LpsA_ld
	global_load_dwordx4 v[60:63], v[10:11], off
	v_lshl_add_u64 v[10:11], v[10:11], 0, s[24:25]
	s_cmp_gt_u32 s4, 12
	s_cbranch_scc0 .LpsA_ld
	global_load_dwordx4 v[64:67], v[10:11], off
	v_lshl_add_u64 v[10:11], v[10:11], 0, s[24:25]
	s_cmp_gt_u32 s4, 13
	s_cbranch_scc0 .LpsA_ld
	global_load_dwordx4 v[68:71], v[10:11], off
	v_lshl_add_u64 v[10:11], v[10:11], 0, s[24:25]
	s_cmp_gt_u32 s4, 14
	s_cbranch_scc0 .LpsA_ld
	global_load_dwordx4 v[72:75], v[10:11], off
	v_lshl_add_u64 v[10:11], v[10:11], 0, s[24:25]
.LpsA_ld:
	s_waitcnt vmcnt(0)
	s_cmp_gt_u32 s4, 0
	s_cbranch_scc0 .LpsA_ad
	v_pk_add_f32 v[8:9], v[8:9], v[18:19]
	v_pk_add_f32 v[6:7], v[6:7], v[16:17]
	s_cmp_gt_u32 s4, 1
	s_cbranch_scc0 .LpsA_ad
	v_pk_add_f32 v[8:9], v[8:9], v[22:23]
	v_pk_add_f32 v[6:7], v[6:7], v[20:21]
	s_cmp_gt_u32 s4, 2
	s_cbranch_scc0 .LpsA_ad
	v_pk_add_f32 v[8:9], v[8:9], v[26:27]
	v_pk_add_f32 v[6:7], v[6:7], v[24:25]
	s_cmp_gt_u32 s4, 3
	s_cbranch_scc0 .LpsA_ad
	v_pk_add_f32 v[8:9], v[8:9], v[30:31]
	v_pk_add_f32 v[6:7], v[6:7], v[28:29]
	s_cmp_gt_u32 s4, 4
	s_cbranch_scc0 .LpsA_ad
	v_pk_add_f32 v[8:9], v[8:9], v[34:35]
	v_pk_add_f32 v[6:7], v[6:7], v[32:33]
	s_cmp_gt_u32 s4, 5
	s_cbranch_scc0 .LpsA_ad
	v_pk_add_f32 v[8:9], v[8:9], v[38:39]
	v_pk_add_f32 v[6:7], v[6:7], v[36:37]
	s_cmp_gt_u32 s4, 6
	s_cbranch_scc0 .LpsA_ad
	v_pk_add_f32 v[8:9], v[8:9], v[42:43]
	v_pk_add_f32 v[6:7], v[6:7], v[40:41]
	s_cmp_gt_u32 s4, 7
	s_cbranch_scc0 .LpsA_ad
	v_pk_add_f32 v[8:9], v[8:9], v[46:47]
	v_pk_add_f32 v[6:7], v[6:7], v[44:45]
	s_cmp_gt_u32 s4, 8
	s_cbranch_scc0 .LpsA_ad
	v_pk_add_f32 v[8:9], v[8:9], v[50:51]
	v_pk_add_f32 v[6:7], v[6:7], v[48:49]
	s_cmp_gt_u32 s4, 9
	s_cbranch_scc0 .LpsA_ad
	v_pk_add_f32 v[8:9], v[8:9], v[54:55]
	v_pk_add_f32 v[6:7], v[6:7], v[52:53]
	s_cmp_gt_u32 s4, 10
	s_cbranch_scc0 .LpsA_ad
	v_pk_add_f32 v[8:9], v[8:9], v[58:59]
	v_pk_add_f32 v[6:7], v[6:7], v[56:57]
	s_cmp_gt_u32 s4, 11
	s_cbranch_scc0 .LpsA_ad
	v_pk_add_f32 v[8:9], v[8:9], v[62:63]
	v_pk_add_f32 v[6:7], v[6:7], v[60:61]
	s_cmp_gt_u32 s4, 12
	s_cbranch_scc0 .LpsA_ad
	v_pk_add_f32 v[8:9], v[8:9], v[66:67]
	v_pk_add_f32 v[6:7], v[6:7], v[64:65]
	s_cmp_gt_u32 s4, 13
	s_cbranch_scc0 .LpsA_ad
	v_pk_add_f32 v[8:9], v[8:9], v[70:71]
	v_pk_add_f32 v[6:7], v[6:7], v[68:69]
	s_cmp_gt_u32 s4, 14
	s_cbranch_scc0 .LpsA_ad
	v_pk_add_f32 v[8:9], v[8:9], v[74:75]
	v_pk_add_f32 v[6:7], v[6:7], v[72:73]
; __device__ __forceinline__ unsigned cvt_pk_bf16(float lo, float hi) { unsigned r; asm volatile("v_cvt_pk_bf16_f32 %0, %1, %2" : "=v"(r) : "v"(lo), "v"(hi)); return r; }
; __device__ __forceinline__ void phase_pool(Frame& F, const Params& p, int j, int first) {
;     ...
;             const f32x4 d = sum / (float)w - h;
;             u32x2 o; o.x = cvt_pk_bf16(d.x, d.y); o.y = cvt_pk_bf16(d.z, d.w);
;             *((u32x2*)(F.HN + (size_t)(ROW_SAMPLE + b) * D) + c4) = o;
;             for (int q = 0; q < 14; ++q) *((f32x4*)(so + (size_t)q * D) + c4) = *((const f32x4*)(st + (size_t)(q + 1) * D) + c4);
;             *((f32x4*)(so + (size_t)14 * D) + c4) = h;
.LpsA_ad:
.LBB0_48:
	v_div_scale_f32 v12, s[14:15], v151, v151, v7
	v_rcp_f32_e32 v13, v12
	s_mul_i32 s4, s96, 0x1e000
	v_readlane_b32 s0, v254, 42
	s_mul_hi_u32 s5, s96, 0x1e000
	v_fma_f32 v14, -v12, v13, 1.0
	v_fmac_f32_e32 v13, v14, v13
	v_div_scale_f32 v14, vcc, v7, v151, v7
	v_mul_f32_e32 v15, v14, v13
	v_fma_f32 v16, -v12, v15, v14
	v_fmac_f32_e32 v15, v16, v13
	v_fma_f32 v12, -v12, v15, v14
	v_div_scale_f32 v14, s[14:15], v151, v151, v6
	v_rcp_f32_e32 v16, v14
	v_div_fmas_f32 v12, v12, v13, v15
	v_div_fixup_f32 v7, v12, v151, v7
	s_add_u32 s4, s0, s4
	v_fma_f32 v12, -v14, v16, 1.0
	v_fmac_f32_e32 v16, v12, v16
	v_div_scale_f32 v12, vcc, v6, v151, v6
	v_mul_f32_e32 v13, v12, v16
	v_fma_f32 v15, -v14, v13, v12
	v_fmac_f32_e32 v13, v15, v16
	v_fma_f32 v12, -v14, v13, v12
	v_div_scale_f32 v14, s[14:15], v151, v151, v9
	v_rcp_f32_e32 v15, v14
	v_div_fmas_f32 v12, v12, v16, v13
	v_div_fixup_f32 v6, v12, v151, v6
	v_readlane_b32 s0, v254, 44
	v_fma_f32 v12, -v14, v15, 1.0
	v_fmac_f32_e32 v15, v12, v15
	v_div_scale_f32 v12, vcc, v9, v151, v9
	v_mul_f32_e32 v13, v12, v15
	v_fma_f32 v16, -v14, v13, v12
	v_fmac_f32_e32 v13, v16, v15
	v_fma_f32 v12, -v14, v13, v12
	v_div_scale_f32 v14, s[14:15], v151, v151, v8
	v_rcp_f32_e32 v16, v14
	v_div_fmas_f32 v12, v12, v15, v13
	v_div_fixup_f32 v9, v12, v151, v9
	s_addc_u32 s5, s0, s5
	v_fma_f32 v12, -v14, v16, 1.0
	v_fmac_f32_e32 v16, v12, v16
	v_div_scale_f32 v12, vcc, v8, v151, v8
	v_mul_f32_e32 v13, v12, v16
	v_fma_f32 v15, -v14, v13, v12
	v_fmac_f32_e32 v13, v15, v16
	v_fma_f32 v12, -v14, v13, v12
	v_div_fmas_f32 v12, v12, v16, v13
	v_mad_u64_u32 v[10:11], s[14:15], s96, v162, v[138:139]
	v_div_fixup_f32 v8, v12, v151, v8
	s_add_i32 s96, s21, 0x1f00
	v_sub_f32_e32 v8, v8, v4
	v_sub_f32_e32 v9, v9, v5
	v_sub_f32_e32 v6, v6, v2
	v_sub_f32_e32 v7, v7, v3
	s_lshl_b64 s[14:15], s[96:97], 12
	v_cvt_pk_bf16_f32 v6, v6, v7
	v_cvt_pk_bf16_f32 v7, v8, v9
	v_lshl_add_u64 v[8:9], v[140:141], 0, s[14:15]
	s_movk_i32 s0, 0x2000
	global_store_dwordx2 v[8:9], v[6:7], off
	v_lshl_add_u64 v[14:15], v[134:135], 4, s[4:5]
	s_mov_b64 s[8:9], 0x2000
	v_lshl_add_u64 v[12:13], v[10:11], 0, s[8:9]
	global_load_dwordx4 v[76:79], v[12:13], off
	v_lshl_add_u64 v[12:13], v[12:13], 0, s[8:9]
	global_load_dwordx4 v[80:83], v[12:13], off
	v_lshl_add_u64 v[12:13], v[12:13], 0, s[8:9]
	global_load_dwordx4 v[84:87], v[12:13], off
	v_lshl_add_u64 v[12:13], v[12:13], 0, s[8:9]
	global_load_dwordx4 v[88:91], v[12:13], off
	v_lshl_add_u64 v[12:13], v[12:13], 0, s[8:9]
	global_load_dwordx4 v[92:95], v[12:13], off
	v_lshl_add_u64 v[12:13], v[12:13], 0, s[8:9]
	global_load_dwordx4 v[96:99], v[12:13], off
	v_lshl_add_u64 v[12:13], v[12:13], 0, s[8:9]
	global_load_dwordx4 v[100:103], v[12:13], off
	v_lshl_add_u64 v[12:13], v[12:13], 0, s[8:9]
	global_load_dwordx4 v[104:107], v[12:13], off
	v_lshl_add_u64 v[12:13], v[12:13], 0, s[8:9]
	global_load_dwordx4 v[108:111], v[12:13], off
	v_lshl_add_u64 v[12:13], v[12:13], 0, s[8:9]
	global_load_dwordx4 v[112:115], v[12:13], off
	v_lshl_add_u64 v[12:13], v[12:13], 0, s[8:9]
	global_load_dwordx4 v[116:119], v[12:13], off
	v_lshl_add_u64 v[12:13], v[12:13], 0, s[8:9]
	global_load_dwordx4 v[120:123], v[12:13], off
	v_lshl_add_u64 v[12:13], v[12:13], 0, s[8:9]
	global_load_dwordx4 v[124:127], v[12:13], off
	v_lshl_add_u64 v[12:13], v[12:13], 0, s[8:9]
	global_load_dwordx4 v[128:131], v[12:13], off
	s_waitcnt vmcnt(0)
	global_store_dwordx4 v[14:15], v[76:79], off
	v_lshl_add_u64 v[14:15], v[14:15], 0, s[8:9]
	global_store_dwordx4 v[14:15], v[80:83], off
	v_lshl_add_u64 v[14:15], v[14:15], 0, s[8:9]
	global_store_dwordx4 v[14:15], v[84:87], off
	v_lshl_add_u64 v[14:15], v[14:15], 0, s[8:9]
	global_store_dwordx4 v[14:15], v[88:91], off
	v_lshl_add_u64 v[14:15], v[14:15], 0, s[8:9]
	global_store_dwordx4 v[14:15], v[92:95], off
	v_lshl_add_u64 v[14:15], v[14:15], 0, s[8:9]
	global_store_dwordx4 v[14:15], v[96:99], off
	v_lshl_add_u64 v[14:15], v[14:15], 0, s[8:9]
	global_store_dwordx4 v[14:15], v[100:103], off
	v_lshl_add_u64 v[14:15], v[14:15], 0, s[8:9]
	global_store_dwordx4 v[14:15], v[104:107], off
	v_lshl_add_u64 v[14:15], v[14:15], 0, s[8:9]
	global_store_dwordx4 v[14:15], v[108:111], off
	v_lshl_add_u64 v[14:15], v[14:15], 0, s[8:9]
	global_store_dwordx4 v[14:15], v[112:115], off
	v_lshl_add_u64 v[14:15], v[14:15], 0, s[8:9]
	global_store_dwordx4 v[14:15], v[116:119], off
	v_lshl_add_u64 v[14:15], v[14:15], 0, s[8:9]
	global_store_dwordx4 v[14:15], v[120:123], off
	v_lshl_add_u64 v[14:15], v[14:15], 0, s[8:9]
	global_store_dwordx4 v[14:15], v[124:127], off
	v_lshl_add_u64 v[14:15], v[14:15], 0, s[8:9]
	global_store_dwordx4 v[14:15], v[128:131], off
	v_lshl_add_u64 v[14:15], v[14:15], 0, s[8:9]
	global_store_dwordx4 v[14:15], v[2:5], off
	s_mov_b64 s[4:5], 0

; __device__ __forceinline__ void phase_pool(Frame& F, const Params& p, int j, int first) {
;     ...
;             if (F.lane == 0) red[F.wave] = s;
;             __syncthreads();
;             s = 0.f;
; #pragma unroll
;             for (int q = 0; q < 8; ++q) s += red[q];
;             const f32x4 h = x * (1.0f / sqrtf(s * (1.0f / D) + EPS)) * g;
;             const float* st = p.in[2] + (size_t)(j * NSAMP + b) * 15 * D;
;             float* so = F.out + O_POOLS + (size_t)(j * NSAMP + b) * 15 * D;
;             const int w = 2 << (F.wave >> 1);
;             f32x4 sum = h;
;             for (int q = 1; q < w; ++q) sum += *((const f32x4*)(st + (size_t)(15 - q) * D) + c4);
.LBB0_1482:
	s_or_b64 exec, exec, s[6:7]
	s_waitcnt lgkmcnt(0)
	s_barrier
	ds_read_b128 v[6:9], v169 offset:256
	ds_read_b128 v[10:13], v169 offset:272
	s_waitcnt lgkmcnt(1)
	v_add_f32_e32 v6, 0, v6
	v_add_f32_e32 v6, v6, v7
	v_add_f32_e32 v6, v6, v8
	v_add_f32_e32 v6, v6, v9
	s_waitcnt lgkmcnt(0)
	v_add_f32_e32 v6, v6, v10
	v_add_f32_e32 v6, v6, v11
	v_add_f32_e32 v6, v6, v12
	v_add_f32_e32 v6, v6, v13
	v_fmamk_f32 v6, v6, 0x3a000000, v204
	v_mul_f32_e32 v7, 0x4f800000, v6
	v_cmp_gt_f32_e32 vcc, s33, v6
	s_nop 1
	v_cndmask_b32_e32 v6, v6, v7, vcc
	v_sqrt_f32_e32 v7, v6
	s_nop 0
	v_add_u32_e32 v8, -1, v7
	v_fma_f32 v10, -v8, v7, v6
	v_add_u32_e32 v9, 1, v7
	v_cmp_ge_f32_e64 s[6:7], 0, v10
	s_nop 1
	v_cndmask_b32_e64 v8, v7, v8, s[6:7]
	v_fma_f32 v7, -v9, v7, v6
	v_cmp_lt_f32_e64 s[6:7], 0, v7
	s_nop 1
	v_cndmask_b32_e64 v7, v8, v9, s[6:7]
	v_mul_f32_e32 v8, 0x37800000, v7
	v_cndmask_b32_e32 v7, v7, v8, vcc
	v_cmp_class_f32_e32 vcc, v6, v205
	s_nop 1
	v_cndmask_b32_e32 v6, v7, v6, vcc
	v_div_scale_f32 v7, s[6:7], v6, v6, 1.0
	v_rcp_f32_e32 v8, v7
	v_readlane_b32 s6, v255, 14
	v_readlane_b32 s7, v255, 15
	v_fma_f32 v9, -v7, v8, 1.0
	v_fmac_f32_e32 v8, v9, v8
	v_div_scale_f32 v9, vcc, 1.0, v6, 1.0
	v_mul_f32_e32 v10, v9, v8
	v_fma_f32 v11, -v7, v10, v9
	v_fmac_f32_e32 v10, v11, v8
	v_fma_f32 v7, -v7, v10, v9
	v_div_fmas_f32 v7, v7, v8, v10
	v_div_fixup_f32 v6, v7, v6, 1.0
	v_pk_mul_f32 v[4:5], v[4:5], v[6:7] op_sel_hi:[1,0]
	v_pk_mul_f32 v[2:3], v[2:3], v[6:7] op_sel_hi:[1,0]
	v_pk_mul_f32 v[4:5], v[68:69], v[4:5]
	v_pk_mul_f32 v[2:3], v[66:67], v[2:3]
	s_andn2_b64 vcc, exec, s[6:7]
	v_mov_b64_e32 v[8:9], v[4:5]
	v_mov_b64_e32 v[6:7], v[2:3]
	s_cbranch_vccnz .LBB0_1485
	v_mad_u64_u32 v[10:11], s[6:7], s17, v220, v[144:145]
	v_mov_b64_e32 v[8:9], v[4:5]
	v_readlane_b32 s6, v255, 32
	v_mov_b64_e32 v[6:7], v[2:3]
	s_movk_i32 s8, 0xe000
	s_mov_b32 s9, -1
	s_cmp_gt_u32 s6, 0
	s_cbranch_scc0 .LpsB_ld
	global_load_dwordx4 v[16:19], v[10:11], off
	v_lshl_add_u64 v[10:11], v[10:11], 0, s[8:9]
	s_cmp_gt_u32 s6, 1
	s_cbranch_scc0 .LpsB_ld
	global_load_dwordx4 v[20:23], v[10:11], off
	v_lshl_add_u64 v[10:11], v[10:11], 0, s[8:9]
	s_cmp_gt_u32 s6, 2
	s_cbranch_scc0 .LpsB_ld
	global_load_dwordx4 v[24:27], v[10:11], off
	v_lshl_add_u64 v[10:11], v[10:11], 0, s[8:9]
	s_cmp_gt_u32 s6, 3
	s_cbranch_scc0 .LpsB_ld
	global_load_dwordx4 v[28:31], v[10:11], off
	v_lshl_add_u64 v[10:11], v[10:11], 0, s[8:9]
	s_cmp_gt_u32 s6, 4
	s_cbranch_scc0 .LpsB_ld
	global_load_dwordx4 v[32:35], v[10:11], off
	v_lshl_add_u64 v[10:11], v[10:11], 0, s[8:9]
	s_cmp_gt_u32 s6, 5
	s_cbranch_scc0 .LpsB_ld
	global_load_dwordx4 v[36:39], v[10:11], off
	v_lshl_add_u64 v[10:11], v[10:11], 0, s[8:9]
	s_cmp_gt_u32 s6, 6
	s_cbranch_scc0 .LpsB_ld
	global_load_dwordx4 v[40:43], v[10:11], off
	v_lshl_add_u64 v[10:11], v[10:11], 0, s[8:9]
	s_cmp_gt_u32 s6, 7
	s_cbranch_scc0 .LpsB_ld
	global_load_dwordx4 v[44:47], v[10:11], off
	v_lshl_add_u64 v[10:11], v[10:11], 0, s[8:9]
	s_cmp_gt_u32 s6, 8
	s_cbranch_scc0 .LpsB_ld
	global_load_dwordx4 v[48:51], v[10:11], off
	v_lshl_add_u64 v[10:11], v[10:11], 0, s[8:9]
	s_cmp_gt_u32 s6, 9
	s_cbranch_scc0 .LpsB_ld
	global_load_dwordx4 v[52:55], v[10:11], off
	v_lshl_add_u64 v[10:11], v[10:11], 0, s[8:9]
	s_cmp_gt_u32 s6, 10
	s_cbranch_scc0 .LpsB_ld
	global_load_dwordx4 v[56:59], v[10:11], off
	v_lshl_add_u64 v[10:11], v[10:11], 0, s[8:9]
	s_cmp_gt_u32 s6, 11
	s_cbranch_scc0 .LpsB_ld
	global_load_dwordx4 v[60:63], v[10:11], off
	v_lshl_add_u64 v[10:11], v[10:11], 0, s[8:9]
	s_cmp_gt_u32 s6, 12
	s_cbranch_scc0 .LpsB_ld
	global_load_dwordx4 v[64:67], v[10:11], off
	v_lshl_add_u64 v[10:11], v[10:11], 0, s[8:9]
	s_cmp_gt_u32 s6, 13
	s_cbranch_scc0 .LpsB_ld
	global_load_dwordx4 v[68:71], v[10:11], off
	v_lshl_add_u64 v[10:11], v[10:11], 0, s[8:9]
	s_cmp_gt_u32 s6, 14
	s_cbranch_scc0 .LpsB_ld
	global_load_dwordx4 v[72:75], v[10:11], off
	v_lshl_add_u64 v[10:11], v[10:11], 0, s[8:9]
.LpsB_ld:
	s_waitcnt vmcnt(0)
	s_cmp_gt_u32 s6, 0
	s_cbranch_scc0 .LpsB_ad
	v_pk_add_f32 v[8:9], v[8:9], v[18:19]
	v_pk_add_f32 v[6:7], v[6:7], v[16:17]
	s_cmp_gt_u32 s6, 1
	s_cbranch_scc0 .LpsB_ad
	v_pk_add_f32 v[8:9], v[8:9], v[22:23]
	v_pk_add_f32 v[6:7], v[6:7], v[20:21]
	s_cmp_gt_u32 s6, 2
	s_cbranch_scc0 .LpsB_ad
	v_pk_add_f32 v[8:9], v[8:9], v[26:27]
	v_pk_add_f32 v[6:7], v[6:7], v[24:25]
	s_cmp_gt_u32 s6, 3
	s_cbranch_scc0 .LpsB_ad
	v_pk_add_f32 v[8:9], v[8:9], v[30:31]
	v_pk_add_f32 v[6:7], v[6:7], v[28:29]
	s_cmp_gt_u32 s6, 4
	s_cbranch_scc0 .LpsB_ad
	v_pk_add_f32 v[8:9], v[8:9], v[34:35]
	v_pk_add_f32 v[6:7], v[6:7], v[32:33]
	s_cmp_gt_u32 s6, 5
	s_cbranch_scc0 .LpsB_ad
	v_pk_add_f32 v[8:9], v[8:9], v[38:39]
	v_pk_add_f32 v[6:7], v[6:7], v[36:37]
	s_cmp_gt_u32 s6, 6
	s_cbranch_scc0 .LpsB_ad
	v_pk_add_f32 v[8:9], v[8:9], v[42:43]
	v_pk_add_f32 v[6:7], v[6:7], v[40:41]
	s_cmp_gt_u32 s6, 7
	s_cbranch_scc0 .LpsB_ad
	v_pk_add_f32 v[8:9], v[8:9], v[46:47]
	v_pk_add_f32 v[6:7], v[6:7], v[44:45]
	s_cmp_gt_u32 s6, 8
	s_cbranch_scc0 .LpsB_ad
	v_pk_add_f32 v[8:9], v[8:9], v[50:51]
	v_pk_add_f32 v[6:7], v[6:7], v[48:49]
	s_cmp_gt_u32 s6, 9
	s_cbranch_scc0 .LpsB_ad
	v_pk_add_f32 v[8:9], v[8:9], v[54:55]
	v_pk_add_f32 v[6:7], v[6:7], v[52:53]
	s_cmp_gt_u32 s6, 10
	s_cbranch_scc0 .LpsB_ad
	v_pk_add_f32 v[8:9], v[8:9], v[58:59]
	v_pk_add_f32 v[6:7], v[6:7], v[56:57]
	s_cmp_gt_u32 s6, 11
	s_cbranch_scc0 .LpsB_ad
	v_pk_add_f32 v[8:9], v[8:9], v[62:63]
	v_pk_add_f32 v[6:7], v[6:7], v[60:61]
	s_cmp_gt_u32 s6, 12
	s_cbranch_scc0 .LpsB_ad
	v_pk_add_f32 v[8:9], v[8:9], v[66:67]
	v_pk_add_f32 v[6:7], v[6:7], v[64:65]
	s_cmp_gt_u32 s6, 13
	s_cbranch_scc0 .LpsB_ad
	v_pk_add_f32 v[8:9], v[8:9], v[70:71]
	v_pk_add_f32 v[6:7], v[6:7], v[68:69]
	s_cmp_gt_u32 s6, 14
	s_cbranch_scc0 .LpsB_ad
	v_pk_add_f32 v[8:9], v[8:9], v[74:75]
	v_pk_add_f32 v[6:7], v[6:7], v[72:73]
; __device__ __forceinline__ unsigned cvt_pk_bf16(float lo, float hi) { unsigned r; asm volatile("v_cvt_pk_bf16_f32 %0, %1, %2" : "=v"(r) : "v"(lo), "v"(hi)); return r; }
; __device__ __forceinline__ void phase_pool(Frame& F, const Params& p, int j, int first) {
;     ...
;             const f32x4 d = sum / (float)w - h;
;             u32x2 o; o.x = cvt_pk_bf16(d.x, d.y); o.y = cvt_pk_bf16(d.z, d.w);
;             *((u32x2*)(F.HN + (size_t)(ROW_SAMPLE + b) * D) + c4) = o;
;             for (int q = 0; q < 14; ++q) *((f32x4*)(so + (size_t)q * D) + c4) = *((const f32x4*)(st + (size_t)(q + 1) * D) + c4);
;             *((f32x4*)(so + (size_t)14 * D) + c4) = h;
.LpsB_ad:
.LBB0_1485:
	s_add_i32 s8, s16, s14
	s_mul_hi_u32 s7, s8, 0x1e000
	s_mul_i32 s6, s8, 0x1e000
	v_mad_u64_u32 v[10:11], s[8:9], s8, v220, v[138:139]
	v_div_scale_f32 v12, s[8:9], v202, v202, v7
	v_rcp_f32_e32 v13, v12
	s_add_u32 s6, s51, s6
	s_addc_u32 s7, s48, s7
	v_fma_f32 v14, -v12, v13, 1.0
	v_fmac_f32_e32 v13, v14, v13
	v_div_scale_f32 v14, vcc, v7, v202, v7
	v_mul_f32_e32 v15, v14, v13
	v_fma_f32 v16, -v12, v15, v14
	v_fmac_f32_e32 v15, v16, v13
	v_fma_f32 v12, -v12, v15, v14
	v_div_fmas_f32 v12, v12, v13, v15
	v_div_fixup_f32 v7, v12, v202, v7
	v_div_scale_f32 v12, s[8:9], v202, v202, v6
	v_rcp_f32_e32 v13, v12
	v_sub_f32_e32 v7, v7, v3
	v_fma_f32 v14, -v12, v13, 1.0
	v_fmac_f32_e32 v13, v14, v13
	v_div_scale_f32 v14, vcc, v6, v202, v6
	v_mul_f32_e32 v15, v14, v13
	v_fma_f32 v16, -v12, v15, v14
	v_fmac_f32_e32 v15, v16, v13
	v_fma_f32 v12, -v12, v15, v14
	v_div_fmas_f32 v12, v12, v13, v15
	v_div_fixup_f32 v6, v12, v202, v6
	v_div_scale_f32 v12, s[8:9], v202, v202, v9
	v_rcp_f32_e32 v13, v12
	v_sub_f32_e32 v6, v6, v2
	v_cvt_pk_bf16_f32 v6, v6, v7
	v_fma_f32 v14, -v12, v13, 1.0
	v_fmac_f32_e32 v13, v14, v13
	v_div_scale_f32 v14, vcc, v9, v202, v9
	v_mul_f32_e32 v15, v14, v13
	v_fma_f32 v16, -v12, v15, v14
	v_fmac_f32_e32 v15, v16, v13
	v_fma_f32 v12, -v12, v15, v14
	v_div_fmas_f32 v12, v12, v13, v15
	v_div_fixup_f32 v9, v12, v202, v9
	v_div_scale_f32 v12, s[8:9], v202, v202, v8
	v_rcp_f32_e32 v13, v12
	v_sub_f32_e32 v9, v9, v5
	s_lshl_b64 s[8:9], s[82:83], 12
	v_fma_f32 v14, -v12, v13, 1.0
	v_fmac_f32_e32 v13, v14, v13
	v_div_scale_f32 v14, vcc, v8, v202, v8
	v_mul_f32_e32 v15, v14, v13
	v_fma_f32 v16, -v12, v15, v14
	v_fmac_f32_e32 v15, v16, v13
	v_fma_f32 v12, -v12, v15, v14
	v_div_fmas_f32 v12, v12, v13, v15
	v_div_fixup_f32 v8, v12, v202, v8
	v_sub_f32_e32 v8, v8, v4
	v_cvt_pk_bf16_f32 v7, v8, v9
	v_lshl_add_u64 v[8:9], v[140:141], 0, s[8:9]
	global_store_dwordx2 v[8:9], v[6:7], off
	v_lshl_add_u64 v[6:7], v[134:135], 4, s[6:7]
	s_mov_b64 s[8:9], 0x2000
	v_lshl_add_u64 v[12:13], v[10:11], 0, s[8:9]
	global_load_dwordx4 v[76:79], v[12:13], off
	v_lshl_add_u64 v[12:13], v[12:13], 0, s[8:9]
	global_load_dwordx4 v[80:83], v[12:13], off
	v_lshl_add_u64 v[12:13], v[12:13], 0, s[8:9]
	global_load_dwordx4 v[84:87], v[12:13], off
	v_lshl_add_u64 v[12:13], v[12:13], 0, s[8:9]
	global_load_dwordx4 v[88:91], v[12:13], off
	v_lshl_add_u64 v[12:13], v[12:13], 0, s[8:9]
	global_load_dwordx4 v[92:95], v[12:13], off
	v_lshl_add_u64 v[12:13], v[12:13], 0, s[8:9]
	global_load_dwordx4 v[96:99], v[12:13], off
	v_lshl_add_u64 v[12:13], v[12:13], 0, s[8:9]
	global_load_dwordx4 v[100:103], v[12:13], off
	v_lshl_add_u64 v[12:13], v[12:13], 0, s[8:9]
	global_load_dwordx4 v[104:107], v[12:13], off
	v_lshl_add_u64 v[12:13], v[12:13], 0, s[8:9]
	global_load_dwordx4 v[108:111], v[12:13], off
	v_lshl_add_u64 v[12:13], v[12:13], 0, s[8:9]
	global_load_dwordx4 v[112:115], v[12:13], off
	v_lshl_add_u64 v[12:13], v[12:13], 0, s[8:9]
	global_load_dwordx4 v[116:119], v[12:13], off
	v_lshl_add_u64 v[12:13], v[12:13], 0, s[8:9]
	global_load_dwordx4 v[120:123], v[12:13], off
	v_lshl_add_u64 v[12:13], v[12:13], 0, s[8:9]
	global_load_dwordx4 v[124:127], v[12:13], off
	v_lshl_add_u64 v[12:13], v[12:13], 0, s[8:9]
	global_load_dwordx4 v[128:131], v[12:13], off
	s_waitcnt vmcnt(0)
	global_store_dwordx4 v[6:7], v[76:79], off
	v_lshl_add_u64 v[6:7], v[6:7], 0, s[8:9]
	global_store_dwordx4 v[6:7], v[80:83], off
	v_lshl_add_u64 v[6:7], v[6:7], 0, s[8:9]
	global_store_dwordx4 v[6:7], v[84:87], off
	v_lshl_add_u64 v[6:7], v[6:7], 0, s[8:9]
	global_store_dwordx4 v[6:7], v[88:91], off
	v_lshl_add_u64 v[6:7], v[6:7], 0, s[8:9]
	global_store_dwordx4 v[6:7], v[92:95], off
	v_lshl_add_u64 v[6:7], v[6:7], 0, s[8:9]
	global_store_dwordx4 v[6:7], v[96:99], off
	v_lshl_add_u64 v[6:7], v[6:7], 0, s[8:9]
	global_store_dwordx4 v[6:7], v[100:103], off
	v_lshl_add_u64 v[6:7], v[6:7], 0, s[8:9]
	global_store_dwordx4 v[6:7], v[104:107], off
	v_lshl_add_u64 v[6:7], v[6:7], 0, s[8:9]
	global_store_dwordx4 v[6:7], v[108:111], off
	v_lshl_add_u64 v[6:7], v[6:7], 0, s[8:9]
	global_store_dwordx4 v[6:7], v[112:115], off
	v_lshl_add_u64 v[6:7], v[6:7], 0, s[8:9]
	global_store_dwordx4 v[6:7], v[116:119], off
	v_lshl_add_u64 v[6:7], v[6:7], 0, s[8:9]
	global_store_dwordx4 v[6:7], v[120:123], off
	v_lshl_add_u64 v[6:7], v[6:7], 0, s[8:9]
	global_store_dwordx4 v[6:7], v[124:127], off
	v_lshl_add_u64 v[6:7], v[6:7], 0, s[8:9]
	global_store_dwordx4 v[6:7], v[128:131], off
	v_lshl_add_u64 v[6:7], v[6:7], 0, s[8:9]
	global_store_dwordx4 v[6:7], v[2:5], off
	s_mov_b64 s[6:7], 0
